# P1: odd XCCs sweep the W_in column blocks starting from block 4 (rotation), on top of the P7 rotation and the P8 round swap
# speedup vs baseline: 1.0246x; 1.0055x over previous
;     __device__ __forceinline__ void tile(int L, int& pm, int& pn) const {
;         const unsigned w = (unsigned)(L & 7) * (2u * fnig) + (unsigned)(L >> 3), gid = __umulhi(w, fmagic), rem = w - gid * fnig; pm = (int)(gid * WGM + (rem & 7u)); pn = (int)(rem >> 3);
;     }
; __global__ void __launch_bounds__(512, 2) layer_fwd(Args args) {
;     ...
;     if (IN(1)) {
;         pg8::Sched S; S.A0 = (const char*)(ws + WS_HN1); S.B0 = (const char*)(ws + WS_WIN); S.A1 = (const char*)(ws + WS_MN); S.B1 = (const char*)(ws + WS_WKV);
;         S.nM0 = M / 256; S.nN0 = hsplit ? 8 : INW / 256; S.n0 = S.nM0 * S.nN0; S.n1 = hsplit ? 0 : (MM / 256) * 4; S.G = F.G; S.c = F.bid; S.tstep = (size_t)256 * D * 2; S.nrep = 1; S.prep();
;         pg8::gemm_phase<pg8::EpiP1, true, true>(F.lds, D, S, EP1);
.LBB0_155:
	s_lshl_b32 s4, s2, 1
	s_and_b32 s4, s4, 14
	s_mul_i32 s4, s69, s4
	s_ashr_i32 s5, s2, 3
	s_add_i32 s4, s4, s5
	s_mul_hi_u32 s6, s86, s4
	s_mul_i32 s7, s69, s6
	s_sub_i32 s4, s4, s7
	s_lshl_b32 s6, s6, 3
	s_and_b32 s5, s5, 7
	s_or_b32 s84, s6, s5
	s_lshr_b32 s40, s4, 3
	s_and_b32 s98, s2, 1
	s_lshl_b32 s98, s98, 2
	s_add_i32 s40, s40, s98
	s_and_b32 s40, s40, 7
	s_mov_b64 s[6:7], -1
	s_mov_b32 s39, 0
	s_mov_b64 s[4:5], 0

;     __device__ __forceinline__ void tile(int L, int& pm, int& pn) const {
;         const unsigned w = (unsigned)(L & 7) * (2u * fnig) + (unsigned)(L >> 3), gid = __umulhi(w, fmagic), rem = w - gid * fnig; pm = (int)(gid * WGM + (rem & 7u)); pn = (int)(rem >> 3);
;     }
;     __device__ __forceinline__ bool next(int i, Unit& u) const {
;         int L = i * G + c;
;         if (nrep > 1) { if (L < n0 * nrep) { const int pass = L / n0; tile(L - pass * n0, u.pm, u.pn); u.kind = (pass + 1 < nrep) ? 2 : 0; return true; } L -= n0 * (nrep - 1); }
;         if (L < n0) { tile(L, u.pm, u.pn); u.pn += pnoff; u.kind = 0; return true; }
.LBB0_165:
	s_andn2_b64 vcc, exec, s[6:7]
	s_cbranch_vccnz .LBB0_167
	s_lshl_b32 s6, s12, 1
	s_and_b32 s6, s6, 14
	s_mul_i32 s6, s6, s69
	s_ashr_i32 s7, s12, 3
	s_add_i32 s6, s6, s7
	s_mul_hi_u32 s12, s6, s86
	s_mul_i32 s38, s69, s12
	s_sub_i32 s6, s6, s38
	s_lshl_b32 s12, s12, 3
	s_and_b32 s7, s7, 7
	s_or_b32 s44, s12, s7
	s_lshr_b32 s42, s6, 3
	s_and_b32 s98, s2, 1
	s_lshl_b32 s98, s98, 2
	s_add_i32 s42, s42, s98
	s_and_b32 s42, s42, 7
	s_mov_b64 s[46:47], -1
	s_mov_b32 s38, 0
